# next-tile coordinates advanced incrementally (pn += G/64 with wrap into pm += 8) instead of the per-tile division chain
# speedup vs baseline: 1.0045x; 1.0006x over previous
.LBB0_515:
	s_add_i32 s36, s36, 1
	s_mul_i32 s8, s36, s46
	s_mul_hi_u32 s9, s36, s77
	s_add_i32 s9, s9, s8
	s_mul_i32 s8, s36, s77
	s_mov_b64 s[84:85], s[12:13]
	s_add_u32 s12, s8, s34
	s_addc_u32 s13, s9, s73
	v_mov_b64_e32 v[0:1], s[42:43]
	v_cmp_ge_i64_e64 s[8:9], s[12:13], v[0:1]
	s_mov_b64 s[78:79], s[48:49]
	s_mov_b32 s20, s69
	s_mov_b32 s25, s80
	v_cmp_lt_i64_e64 s[10:11], s[12:13], v[0:1]
	s_and_b64 vcc, exec, s[8:9]
	s_cbranch_vccnz .LBB0_517
	s_lshr_b32 s12, s77, 6
	s_add_i32 s80, s80, s12
	s_lshr_b32 s13, s37, 3
	s_cmp_ge_i32 s80, s13
	s_cbranch_scc0 .Lti_done
	s_sub_i32 s80, s80, s13
	s_add_i32 s69, s69, 8
	s_cmp_ge_i32 s80, s13
	s_cbranch_scc0 .Lti_done
	s_sub_i32 s80, s80, s13
	s_add_i32 s69, s69, 8
.Lti_done:
.LBB0_517:
	v_cndmask_b32_e64 v0, 0, 1, s[10:11]
	v_cmp_ne_u32_e64 s[12:13], 1, v0
	s_andn2_b64 vcc, exec, s[10:11]
	s_mov_b64 s[48:49], s[78:79]
	s_cbranch_vccnz .LBB0_519
	s_ashr_i32 s10, s69, 31
	s_mul_hi_u32 s11, s30, s69
	s_mul_i32 s10, s30, s10
	s_add_i32 s10, s11, s10
	s_mul_i32 s11, s31, s69
	s_add_i32 s10, s10, s11
	s_mul_i32 s11, s30, s69
	s_add_u32 s48, s92, s11
	s_addc_u32 s49, s93, s10
